# spatial gating: causal-weight tile loads issued together with the operand loads at unit start (one exposed memory latency less per unit)
# baseline (speedup 1.0000x reference)
; __device__ __forceinline__ float hsum4(f32x4 a) { return (a[0] + a[1]) + (a[2] + a[3]); }
; __device__ __forceinline__ void sg_phase(const float* sgw, const float* sgb, const float* sgn, const bf16_t* U, const bf16_t* VTc, const float* ssv, bf16_t* GATED, LAS unsigned char* lds, int G) {
;     ...
;     for (int unit = blockIdx.x; unit < 2048; unit += G) {
;         const int chunk = unit >> 2, g = unit & 3, tok0 = chunk * 128;
;         bf16x8 bfr[2][4];
;         const bf16_t* vb = VTc + ((size_t)chunk * 1024 + g * 256 + 32 * wid + 8 * (fr >> 2) + (fr & 3)) * 128 + 8 * fq;
; #pragma unroll
;         for (int nf = 0; nf < 2; ++nf)
; #pragma unroll
;             for (int kk = 0; kk < 4; ++kk) bfr[nf][kk] = *(const bf16x8*)(vb + (size_t)nf * 4 * 128 + 32 * kk);
;         u32x4 uu[8];
;         const size_t rowoff = (size_t)(tok0 + fr) * 1024 + g * 256 + 32 * wid + 8 * fq;
; #pragma unroll
;         for (int tf = 0; tf < 8; ++tf) uu[tf] = *(const u32x4*)(U + rowoff + (size_t)tf * 16 * 1024);
;         if (tid < 128) { const f32x4* p = (const f32x4*)(ssv + (size_t)(tok0 + tid) * 8); tab[tid] = __builtin_amdgcn_rsqf((pg8::hsum4(p[0]) + pg8::hsum4(p[1])) * (1.0f / 1024.0f) + EPS); }
;         __syncthreads();
;         {
;             const int t = tid >> 2, sg0 = 32 * (tid & 3);
;             if (sg0 <= t) {
;                 const float* wrow = sgw + ((size_t)g * 128 + t) * 128 + sg0;
; #pragma unroll
;                 for (int c = 0; c < 4; ++c) { const f32x4 wa = *(const f32x4*)(wrow + 8 * c), wb = *(const f32x4*)(wrow + 8 * c + 4); float av[8];
.LBB0_521:
	s_ashr_i32 s94, s2, 2
	s_ashr_i32 s95, s94, 31
	s_lshl_b64 vcc, s[94:95], 18
	s_lshl_b32 s94, s94, 7
	s_and_b32 s93, s2, 3
	s_waitcnt vmcnt(5)
	v_or_b32_e32 v24, s94, v89
	s_lshl_b32 s78, s93, 8
	v_ashrrev_i32_e32 v25, 31, v24
	v_lshlrev_b64 v[24:25], 10, v[24:25]
	v_lshl_add_u64 v[26:27], v[78:79], 0, s[78:79]
	v_lshl_add_u64 v[84:85], v[26:27], 0, v[24:25]
	v_lshl_add_u64 v[0:1], v[74:75], 0, s[78:79]
	v_lshl_add_u64 v[24:25], v[84:85], 1, s[0:1]
	v_lshlrev_b64 v[0:1], 8, v[0:1]
	v_lshl_add_u64 v[2:3], v[76:77], 0, vcc
	v_add_co_u32_e32 v26, vcc, 0x8000, v24
	v_lshl_add_u64 v[0:1], v[2:3], 0, v[0:1]
	s_nop 0
	v_addc_co_u32_e32 v27, vcc, 0, v25, vcc
	global_load_dwordx4 v[40:43], v[0:1], off
	global_load_dwordx4 v[20:23], v[0:1], off offset:64
	global_load_dwordx4 v[12:15], v[0:1], off offset:128
	global_load_dwordx4 v[4:7], v[0:1], off offset:192
	global_load_dwordx4 v[28:31], v[0:1], off offset:1024
	global_load_dwordx4 v[16:19], v[0:1], off offset:1088
	global_load_dwordx4 v[8:11], v[0:1], off offset:1152
	s_nop 0
	global_load_dwordx4 v[0:3], v[0:1], off offset:1216
	s_nop 0
	global_load_dwordx4 v[70:73], v[24:25], off
	global_load_dwordx4 v[66:69], v[26:27], off
	v_add_co_u32_e32 v26, vcc, s11, v24
	s_mov_b32 s10, s76
	s_nop 0
	v_addc_co_u32_e32 v27, vcc, 0, v25, vcc
	v_add_co_u32_e32 v32, vcc, 0x18000, v24
	s_nop 1
	v_addc_co_u32_e32 v33, vcc, 0, v25, vcc
	global_load_dwordx4 v[60:63], v[26:27], off
	global_load_dwordx4 v[56:59], v[32:33], off
	v_add_co_u32_e32 v26, vcc, 0x20000, v24
	s_nop 1
	v_addc_co_u32_e32 v27, vcc, 0, v25, vcc
	v_add_co_u32_e32 v32, vcc, 0x28000, v24
	s_nop 1
	v_addc_co_u32_e32 v33, vcc, 0, v25, vcc
	global_load_dwordx4 v[52:55], v[26:27], off
	global_load_dwordx4 v[36:39], v[32:33], off
	v_add_co_u32_e32 v26, vcc, 0x30000, v24
	s_nop 1
	v_addc_co_u32_e32 v27, vcc, 0, v25, vcc
	v_add_co_u32_e32 v24, vcc, 0x38000, v24
	s_nop 1
	v_addc_co_u32_e32 v25, vcc, 0, v25, vcc
	global_load_dwordx4 v[32:35], v[26:27], off
	s_nop 0
	global_load_dwordx4 v[24:27], v[24:25], off
	s_lshl_b32 s76, s93, 7
	s_and_saveexec_b64 s[100:101], s[8:9]
	v_add_u32_e32 v178, s76, v91
	v_mov_b32_e32 v179, 0
	v_lshlrev_b64 v[178:179], 9, v[178:179]
	v_lshl_add_u64 v[206:207], v[80:81], 0, v[178:179]
	global_load_dwordx4 v[120:123], v[206:207], off
	global_load_dwordx4 v[124:127], v[206:207], off offset:16
	global_load_dwordx4 v[128:131], v[206:207], off offset:32
	global_load_dwordx4 v[132:135], v[206:207], off offset:48
	global_load_dwordx4 v[136:139], v[206:207], off offset:64
	global_load_dwordx4 v[140:143], v[206:207], off offset:80
	global_load_dwordx4 v[144:147], v[206:207], off offset:96
	global_load_dwordx4 v[148:151], v[206:207], off offset:112
	s_mov_b64 exec, s[100:101]
	s_and_saveexec_b64 vcc, s[6:7]
	s_cbranch_execz .LBB0_523
	v_add_u32_e32 v44, s94, v88
	v_ashrrev_i32_e32 v45, 31, v44
	v_readlane_b32 s76, v255, 7
	v_lshlrev_b64 v[44:45], 5, v[44:45]
	v_readlane_b32 s77, v255, 8
	s_nop 1
	v_lshl_add_u64 v[48:49], s[76:77], 0, v[44:45]
	global_load_dwordx4 v[44:47], v[48:49], off
	s_nop 0
	global_load_dwordx4 v[48:51], v[48:49], off offset:16
	s_waitcnt vmcnt(1)
	v_mov_b32_e32 v86, v44
	s_waitcnt vmcnt(0)
	v_mov_b32_e32 v87, v48
	v_mov_b32_e32 v48, v45
	v_mov_b32_e32 v44, v46
	v_mov_b32_e32 v45, v50
	v_mov_b32_e32 v50, v47
	v_pk_add_f32 v[46:47], v[86:87], v[48:49]
	v_pk_add_f32 v[44:45], v[44:45], v[50:51]
	s_nop 0
	v_pk_add_f32 v[44:45], v[46:47], v[44:45]
	s_nop 0
	v_add_f32_e32 v44, v44, v45
	v_fmamk_f32 v44, v44, 0x3a800000, v232
	v_rsq_f32_e32 v44, v44
	ds_write_b32 v90, v44 offset:36864
; #define LAS __attribute__((address_space(3)))
; __device__ __forceinline__ u32x4 pack8(const float* v) { u32x4 w; w.x = cvt_pk_bf16(v[0], v[1]); w.y = cvt_pk_bf16(v[2], v[3]); w.z = cvt_pk_bf16(v[4], v[5]); w.w = cvt_pk_bf16(v[6], v[7]); return w; }
; __device__ __forceinline__ void sg_phase(const float* sgw, const float* sgb, const float* sgn, const bf16_t* U, const bf16_t* VTc, const float* ssv, bf16_t* GATED, LAS unsigned char* lds, int G) {
;     ...
;             const int t = tid >> 2, sg0 = 32 * (tid & 3);
;             if (sg0 <= t) {
;                 const float* wrow = sgw + ((size_t)g * 128 + t) * 128 + sg0;
; #pragma unroll
;                 for (int c = 0; c < 4; ++c) { const f32x4 wa = *(const f32x4*)(wrow + 8 * c), wb = *(const f32x4*)(wrow + 8 * c + 4); float av[8];
; #pragma unroll
;                     for (int j = 0; j < 8; ++j) { const int s = sg0 + 8 * c + j; const float w = j < 4 ? wa[j] : wb[j - 4]; av[j] = (s <= t) ? w * tab[s] : 0.f; }
;                     *(LAS u32x4*)(lds + t * WROW + (sg0 + 8 * c) * 2) = pack8(av); }
;             }
.LBB0_523:
	s_or_b64 exec, exec, vcc
	s_lshl_b32 s93, s93, 7
	s_waitcnt lgkmcnt(0)
	s_barrier
	s_and_saveexec_b64 vcc, s[8:9]
	s_cbranch_execz .LBB0_520
	v_readlane_b32 s76, v255, 9
	v_readlane_b32 s77, v255, 10
	ds_read_b32 v152, v92 offset:36864
	ds_read_b32 v153, v92 offset:36868
	ds_read_b32 v154, v92 offset:36872
	ds_read_b32 v155, v92 offset:36876
	ds_read_b32 v156, v92 offset:36880
	ds_read_b32 v157, v92 offset:36884
	ds_read_b32 v158, v92 offset:36888
	ds_read_b32 v159, v92 offset:36892
	ds_read_b32 v160, v92 offset:36896
	ds_read_b32 v161, v92 offset:36900
	ds_read_b32 v162, v92 offset:36904
	ds_read_b32 v163, v92 offset:36908
	ds_read_b32 v164, v92 offset:36912
	ds_read_b32 v165, v92 offset:36916
	ds_read_b32 v166, v92 offset:36920
	ds_read_b32 v167, v92 offset:36924
	ds_read_b32 v168, v92 offset:36928
	ds_read_b32 v169, v92 offset:36932
	ds_read_b32 v170, v92 offset:36936
	ds_read_b32 v171, v92 offset:36940
	ds_read_b32 v172, v92 offset:36944
	ds_read_b32 v173, v92 offset:36948
	ds_read_b32 v174, v92 offset:36952
	ds_read_b32 v175, v92 offset:36956
	ds_read_b32 v176, v92 offset:36960
	ds_read_b32 v177, v92 offset:36964
	ds_read_b32 v178, v92 offset:36968
	ds_read_b32 v179, v92 offset:36972
	ds_read_b32 v202, v92 offset:36976
	ds_read_b32 v203, v92 offset:36980
	ds_read_b32 v204, v92 offset:36984
	ds_read_b32 v205, v92 offset:36988
	s_waitcnt vmcnt(0) lgkmcnt(0)
	v_mul_f32_e32 v120, v120, v152
	v_mul_f32_e32 v121, v121, v153
	v_mul_f32_e32 v122, v122, v154
	v_mul_f32_e32 v123, v123, v155
	v_mul_f32_e32 v124, v124, v156
	v_mul_f32_e32 v125, v125, v157
	v_mul_f32_e32 v126, v126, v158
	v_mul_f32_e32 v127, v127, v159
	v_mul_f32_e32 v128, v128, v160
	v_mul_f32_e32 v129, v129, v161
	v_mul_f32_e32 v130, v130, v162
	v_mul_f32_e32 v131, v131, v163
	v_mul_f32_e32 v132, v132, v164
	v_mul_f32_e32 v133, v133, v165
	v_mul_f32_e32 v134, v134, v166
	v_mul_f32_e32 v135, v135, v167
	v_mul_f32_e32 v136, v136, v168
	v_mul_f32_e32 v137, v137, v169
	v_mul_f32_e32 v138, v138, v170
	v_mul_f32_e32 v139, v139, v171
	v_mul_f32_e32 v140, v140, v172
	v_mul_f32_e32 v141, v141, v173
	v_mul_f32_e32 v142, v142, v174
	v_mul_f32_e32 v143, v143, v175
	v_mul_f32_e32 v144, v144, v176
	v_mul_f32_e32 v145, v145, v177
	v_mul_f32_e32 v146, v146, v178
	v_mul_f32_e32 v147, v147, v179
	v_mul_f32_e32 v148, v148, v202
	v_mul_f32_e32 v149, v149, v203
	v_mul_f32_e32 v150, v150, v204
	v_mul_f32_e32 v151, v151, v205
	v_cndmask_b32_e64 v121, 0, v121, s[76:77]
	v_cndmask_b32_e64 v122, 0, v122, s[12:13]
	v_cndmask_b32_e64 v123, 0, v123, s[14:15]
	v_cndmask_b32_e64 v124, 0, v124, s[16:17]
	v_cndmask_b32_e64 v125, 0, v125, s[18:19]
	v_cndmask_b32_e64 v126, 0, v126, s[20:21]
	v_cndmask_b32_e64 v127, 0, v127, s[22:23]
	v_cndmask_b32_e64 v128, 0, v128, s[24:25]
	v_cndmask_b32_e64 v129, 0, v129, s[26:27]
	v_cndmask_b32_e64 v130, 0, v130, s[28:29]
	v_cndmask_b32_e64 v131, 0, v131, s[30:31]
	v_cndmask_b32_e64 v132, 0, v132, s[34:35]
	v_cndmask_b32_e64 v133, 0, v133, s[36:37]
	v_cndmask_b32_e64 v134, 0, v134, s[38:39]
	v_cndmask_b32_e64 v135, 0, v135, s[40:41]
	v_cndmask_b32_e64 v136, 0, v136, s[42:43]
	v_cndmask_b32_e64 v137, 0, v137, s[44:45]
	v_cndmask_b32_e64 v138, 0, v138, s[46:47]
	v_cndmask_b32_e64 v139, 0, v139, s[48:49]
	v_cndmask_b32_e64 v140, 0, v140, s[50:51]
	v_cndmask_b32_e64 v141, 0, v141, s[52:53]
	v_cndmask_b32_e64 v142, 0, v142, s[54:55]
	v_cndmask_b32_e64 v143, 0, v143, s[56:57]
	v_cndmask_b32_e64 v144, 0, v144, s[58:59]
	v_cndmask_b32_e64 v145, 0, v145, s[60:61]
	v_cndmask_b32_e64 v146, 0, v146, s[62:63]
	v_cndmask_b32_e64 v147, 0, v147, s[64:65]
	v_cndmask_b32_e64 v148, 0, v148, s[66:67]
	v_cndmask_b32_e64 v149, 0, v149, s[68:69]
	v_cndmask_b32_e64 v150, 0, v150, s[70:71]
	v_cndmask_b32_e64 v151, 0, v151, s[72:73]
	v_cvt_pk_bf16_f32 v152, v120, v121
	v_cvt_pk_bf16_f32 v153, v122, v123
	v_cvt_pk_bf16_f32 v154, v124, v125
	v_cvt_pk_bf16_f32 v155, v126, v127
	v_cvt_pk_bf16_f32 v156, v128, v129
	v_cvt_pk_bf16_f32 v157, v130, v131
	v_cvt_pk_bf16_f32 v158, v132, v133
	v_cvt_pk_bf16_f32 v159, v134, v135
	v_cvt_pk_bf16_f32 v160, v136, v137
	v_cvt_pk_bf16_f32 v161, v138, v139
	v_cvt_pk_bf16_f32 v162, v140, v141
	v_cvt_pk_bf16_f32 v163, v142, v143
	v_cvt_pk_bf16_f32 v164, v144, v145
	v_cvt_pk_bf16_f32 v165, v146, v147
	v_cvt_pk_bf16_f32 v166, v148, v149
	v_cvt_pk_bf16_f32 v167, v150, v151
	ds_write_b128 v94, v[152:155]
	ds_write_b128 v94, v[156:159] offset:16
	ds_write_b128 v94, v[160:163] offset:32
	ds_write_b128 v94, v[164:167] offset:48
	s_branch .LBB0_520
